# adds: P5 normaliser recurrence (workgroups 0..1) chunk values requested at the start of the phase
# speedup vs baseline: 1.0213x; 1.0103x over previous
; __device__ __forceinline__ void mlstm_state_scan(const Frame& F) {
;     ...
;     for (int e = gt; e < 1024; e += GT) { const int h = e >> 8; const float* UN = (const float*)(F.ws + WS_UN); float* NST = (float*)(F.ws + WS_NST);
;         float n = 0.f;
;         for (int c = 0; c < NCH; ++c) { NST[c * 1024 + e] = n; n = n * sdec[h * 32 + c] + UN[c * 1024 + e]; }
.LBB0_672:
	s_cmp_lt_i32 s86, 6
	s_cselect_b64 s[2:3], -1, 0
	s_waitcnt lgkmcnt(0)
	s_and_b64 s[18:19], s[2:3], s[0:1]
	s_andn2_b64 vcc, exec, s[18:19]
	s_cbranch_vccnz .LBB0_686
	s_cmpk_gt_u32 s33, 1
	s_cbranch_scc1 .Lmy_p5nst_skip
	v_lshl_add_u32 v202, s33, 9, v144
	v_lshlrev_b32_e32 v202, 2, v202
	s_add_u32 s20, s84, 0x19dc0100
	s_addc_u32 s21, s85, 0
	global_load_dword v170, v202, s[20:21]
	s_add_u32 s20, s20, 0x1000
	s_addc_u32 s21, s21, 0
	global_load_dword v171, v202, s[20:21]
	s_add_u32 s20, s20, 0x1000
	s_addc_u32 s21, s21, 0
	global_load_dword v172, v202, s[20:21]
	s_add_u32 s20, s20, 0x1000
	s_addc_u32 s21, s21, 0
	global_load_dword v173, v202, s[20:21]
	s_add_u32 s20, s20, 0x1000
	s_addc_u32 s21, s21, 0
	global_load_dword v174, v202, s[20:21]
	s_add_u32 s20, s20, 0x1000
	s_addc_u32 s21, s21, 0
	global_load_dword v175, v202, s[20:21]
	s_add_u32 s20, s20, 0x1000
	s_addc_u32 s21, s21, 0
	global_load_dword v176, v202, s[20:21]
	s_add_u32 s20, s20, 0x1000
	s_addc_u32 s21, s21, 0
	global_load_dword v177, v202, s[20:21]
	s_add_u32 s20, s20, 0x1000
	s_addc_u32 s21, s21, 0
	global_load_dword v178, v202, s[20:21]
	s_add_u32 s20, s20, 0x1000
	s_addc_u32 s21, s21, 0
	global_load_dword v179, v202, s[20:21]
	s_add_u32 s20, s20, 0x1000
	s_addc_u32 s21, s21, 0
	global_load_dword v180, v202, s[20:21]
	s_add_u32 s20, s20, 0x1000
	s_addc_u32 s21, s21, 0
	global_load_dword v181, v202, s[20:21]
	s_add_u32 s20, s20, 0x1000
	s_addc_u32 s21, s21, 0
	global_load_dword v182, v202, s[20:21]
	s_add_u32 s20, s20, 0x1000
	s_addc_u32 s21, s21, 0
	global_load_dword v183, v202, s[20:21]
	s_add_u32 s20, s20, 0x1000
	s_addc_u32 s21, s21, 0
	global_load_dword v184, v202, s[20:21]
	s_add_u32 s20, s20, 0x1000
	s_addc_u32 s21, s21, 0
	global_load_dword v185, v202, s[20:21]
	s_add_u32 s20, s20, 0x1000
	s_addc_u32 s21, s21, 0
	global_load_dword v186, v202, s[20:21]
	s_add_u32 s20, s20, 0x1000
	s_addc_u32 s21, s21, 0
	global_load_dword v187, v202, s[20:21]
	s_add_u32 s20, s20, 0x1000
	s_addc_u32 s21, s21, 0
	global_load_dword v188, v202, s[20:21]
	s_add_u32 s20, s20, 0x1000
	s_addc_u32 s21, s21, 0
	global_load_dword v189, v202, s[20:21]
	s_add_u32 s20, s20, 0x1000
	s_addc_u32 s21, s21, 0
	global_load_dword v190, v202, s[20:21]
	s_add_u32 s20, s20, 0x1000
	s_addc_u32 s21, s21, 0
	global_load_dword v191, v202, s[20:21]
	s_add_u32 s20, s20, 0x1000
	s_addc_u32 s21, s21, 0
	global_load_dword v192, v202, s[20:21]
	s_add_u32 s20, s20, 0x1000
	s_addc_u32 s21, s21, 0
	global_load_dword v193, v202, s[20:21]
	s_add_u32 s20, s20, 0x1000
	s_addc_u32 s21, s21, 0
	global_load_dword v194, v202, s[20:21]
	s_add_u32 s20, s20, 0x1000
	s_addc_u32 s21, s21, 0
	global_load_dword v195, v202, s[20:21]
	s_add_u32 s20, s20, 0x1000
	s_addc_u32 s21, s21, 0
	global_load_dword v196, v202, s[20:21]
	s_add_u32 s20, s20, 0x1000
	s_addc_u32 s21, s21, 0
	global_load_dword v197, v202, s[20:21]
	s_add_u32 s20, s20, 0x1000
	s_addc_u32 s21, s21, 0
	global_load_dword v198, v202, s[20:21]
	s_add_u32 s20, s20, 0x1000
	s_addc_u32 s21, s21, 0
	global_load_dword v199, v202, s[20:21]
	s_add_u32 s20, s20, 0x1000
	s_addc_u32 s21, s21, 0
	global_load_dword v200, v202, s[20:21]
	s_add_u32 s20, s20, 0x1000
	s_addc_u32 s21, s21, 0
	global_load_dword v201, v202, s[20:21]
; __device__ __forceinline__ void mlstm_state_scan(const Frame& F) {
;     ...
;     if (F.tid < 128) { const int h = F.tid >> 5, c = F.tid & 31; const float* MR = MRb + h * SP; sdec[F.tid] = expf((c == 0 ? 0.f : MR[c * LC - 1]) - MR[c * LC + LC - 1]); }
;     __syncthreads();
;     const int gt = F.bid * 512 + F.tid, GT = F.G * 512;
;     typedef float f32x2 __attribute__((ext_vector_type(2)));
;     for (int e2 = gt; e2 < 131072; e2 += GT) { const int h = e2 >> 15;
;         f32x2 C = (f32x2){0.f, 0.f};
; #pragma unroll 1
;         for (int c0 = 0; c0 < NCH; c0 += 8) { f32x2 u[8];
; #pragma unroll
;             for (int k = 0; k < 8; ++k) u[k] = *(const f32x2*)(U + (size_t)(c0 + k) * 262144 + (size_t)e2 * 2);
.Lmy_p5nst_skip:
	v_lshl_add_u32 v104, s33, 9, v144
	v_lshlrev_b32_e32 v104, 3, v104
	v_mov_b32_e32 v105, 0
	v_lshl_add_u64 v[12:13], s[84:85], 0, v[104:105]
	v_add_co_u32_e32 v14, vcc, 0x17dc0000, v12
	s_nop 1
	v_addc_co_u32_e32 v15, vcc, 0, v13, vcc
	global_load_dwordx2 v[40:41], v[14:15], off offset:256
	v_add_co_u32_e32 v14, vcc, 0x17ec0000, v12
	s_nop 1
	v_addc_co_u32_e32 v15, vcc, 0, v13, vcc
	global_load_dwordx2 v[42:43], v[14:15], off offset:256
	v_add_co_u32_e32 v14, vcc, 0x17fc0000, v12
	s_nop 1
	v_addc_co_u32_e32 v15, vcc, 0, v13, vcc
	global_load_dwordx2 v[44:45], v[14:15], off offset:256
	v_add_co_u32_e32 v14, vcc, 0x180c0000, v12
	s_nop 1
	v_addc_co_u32_e32 v15, vcc, 0, v13, vcc
	global_load_dwordx2 v[46:47], v[14:15], off offset:256
	v_add_co_u32_e32 v14, vcc, 0x181c0000, v12
	s_nop 1
	v_addc_co_u32_e32 v15, vcc, 0, v13, vcc
	global_load_dwordx2 v[48:49], v[14:15], off offset:256
	v_add_co_u32_e32 v14, vcc, 0x182c0000, v12
	s_nop 1
	v_addc_co_u32_e32 v15, vcc, 0, v13, vcc
	global_load_dwordx2 v[50:51], v[14:15], off offset:256
	v_add_co_u32_e32 v14, vcc, 0x183c0000, v12
	s_nop 1
	v_addc_co_u32_e32 v15, vcc, 0, v13, vcc
	global_load_dwordx2 v[52:53], v[14:15], off offset:256
	v_add_co_u32_e32 v14, vcc, 0x184c0000, v12
	s_nop 1
	v_addc_co_u32_e32 v15, vcc, 0, v13, vcc
	global_load_dwordx2 v[54:55], v[14:15], off offset:256
	v_add_co_u32_e32 v14, vcc, 0x185c0000, v12
	s_nop 1
	v_addc_co_u32_e32 v15, vcc, 0, v13, vcc
	global_load_dwordx2 v[56:57], v[14:15], off offset:256
	v_add_co_u32_e32 v14, vcc, 0x186c0000, v12
	s_nop 1
	v_addc_co_u32_e32 v15, vcc, 0, v13, vcc
	global_load_dwordx2 v[58:59], v[14:15], off offset:256
	v_add_co_u32_e32 v14, vcc, 0x187c0000, v12
	s_nop 1
	v_addc_co_u32_e32 v15, vcc, 0, v13, vcc
	global_load_dwordx2 v[60:61], v[14:15], off offset:256
	v_add_co_u32_e32 v14, vcc, 0x188c0000, v12
	s_nop 1
	v_addc_co_u32_e32 v15, vcc, 0, v13, vcc
	global_load_dwordx2 v[62:63], v[14:15], off offset:256
	v_add_co_u32_e32 v14, vcc, 0x189c0000, v12
	s_nop 1
	v_addc_co_u32_e32 v15, vcc, 0, v13, vcc
	global_load_dwordx2 v[64:65], v[14:15], off offset:256
	v_add_co_u32_e32 v14, vcc, 0x18ac0000, v12
	s_nop 1
	v_addc_co_u32_e32 v15, vcc, 0, v13, vcc
	global_load_dwordx2 v[66:67], v[14:15], off offset:256
	v_add_co_u32_e32 v14, vcc, 0x18bc0000, v12
	s_nop 1
	v_addc_co_u32_e32 v15, vcc, 0, v13, vcc
	global_load_dwordx2 v[68:69], v[14:15], off offset:256
	v_add_co_u32_e32 v14, vcc, 0x18cc0000, v12
	s_nop 1
	v_addc_co_u32_e32 v15, vcc, 0, v13, vcc
	global_load_dwordx2 v[70:71], v[14:15], off offset:256
	v_add_co_u32_e32 v14, vcc, 0x18dc0000, v12
	s_nop 1
	v_addc_co_u32_e32 v15, vcc, 0, v13, vcc
	global_load_dwordx2 v[72:73], v[14:15], off offset:256
	v_add_co_u32_e32 v14, vcc, 0x18ec0000, v12
	s_nop 1
	v_addc_co_u32_e32 v15, vcc, 0, v13, vcc
	global_load_dwordx2 v[74:75], v[14:15], off offset:256
	v_add_co_u32_e32 v14, vcc, 0x18fc0000, v12
	s_nop 1
	v_addc_co_u32_e32 v15, vcc, 0, v13, vcc
	global_load_dwordx2 v[76:77], v[14:15], off offset:256
	v_add_co_u32_e32 v14, vcc, 0x190c0000, v12
	s_nop 1
	v_addc_co_u32_e32 v15, vcc, 0, v13, vcc
	global_load_dwordx2 v[78:79], v[14:15], off offset:256
	v_add_co_u32_e32 v14, vcc, 0x191c0000, v12
	s_nop 1
	v_addc_co_u32_e32 v15, vcc, 0, v13, vcc
	global_load_dwordx2 v[80:81], v[14:15], off offset:256
	v_add_co_u32_e32 v14, vcc, 0x192c0000, v12
	s_nop 1
	v_addc_co_u32_e32 v15, vcc, 0, v13, vcc
	global_load_dwordx2 v[82:83], v[14:15], off offset:256
	v_add_co_u32_e32 v14, vcc, 0x193c0000, v12
	s_nop 1
	v_addc_co_u32_e32 v15, vcc, 0, v13, vcc
	global_load_dwordx2 v[84:85], v[14:15], off offset:256
	v_add_co_u32_e32 v14, vcc, 0x194c0000, v12
	s_nop 1
	v_addc_co_u32_e32 v15, vcc, 0, v13, vcc
	global_load_dwordx2 v[86:87], v[14:15], off offset:256
	v_add_co_u32_e32 v14, vcc, 0x195c0000, v12
	s_nop 1
	v_addc_co_u32_e32 v15, vcc, 0, v13, vcc
	global_load_dwordx2 v[88:89], v[14:15], off offset:256
	v_add_co_u32_e32 v14, vcc, 0x196c0000, v12
	s_nop 1
	v_addc_co_u32_e32 v15, vcc, 0, v13, vcc
	global_load_dwordx2 v[90:91], v[14:15], off offset:256
	v_add_co_u32_e32 v14, vcc, 0x197c0000, v12
	s_nop 1
	v_addc_co_u32_e32 v15, vcc, 0, v13, vcc
	global_load_dwordx2 v[92:93], v[14:15], off offset:256
	v_add_co_u32_e32 v14, vcc, 0x198c0000, v12
	s_nop 1
	v_addc_co_u32_e32 v15, vcc, 0, v13, vcc
	global_load_dwordx2 v[94:95], v[14:15], off offset:256
	v_add_co_u32_e32 v14, vcc, 0x199c0000, v12
	s_nop 1
	v_addc_co_u32_e32 v15, vcc, 0, v13, vcc
	global_load_dwordx2 v[96:97], v[14:15], off offset:256
	v_add_co_u32_e32 v14, vcc, 0x19ac0000, v12
	s_nop 1
	v_addc_co_u32_e32 v15, vcc, 0, v13, vcc
	global_load_dwordx2 v[98:99], v[14:15], off offset:256
	v_add_co_u32_e32 v14, vcc, 0x19bc0000, v12
	s_nop 1
	v_addc_co_u32_e32 v15, vcc, 0, v13, vcc
	global_load_dwordx2 v[100:101], v[14:15], off offset:256
	v_add_co_u32_e32 v14, vcc, 0x19cc0000, v12
	s_nop 1
	v_addc_co_u32_e32 v15, vcc, 0, v13, vcc
	global_load_dwordx2 v[102:103], v[14:15], off offset:256
	s_movk_i32 s0, 0x80
	v_cmp_gt_u32_e32 vcc, s0, v144
	s_and_saveexec_b64 s[0:1], vcc
	s_cbranch_execz .LBB0_677
	s_waitcnt vmcnt(0)
	v_lshlrev_b32_e32 v0, 10, v144
	v_and_b32_e32 v0, 0x18000, v0
	v_mov_b32_e32 v1, 0
	v_and_b32_e32 v6, 31, v144
	v_lshl_add_u64 v[2:3], s[84:85], 0, v[0:1]
	s_mov_b64 s[2:3], 0x17da0100
	v_mov_b64_e32 v[4:5], 0
	v_lshl_add_u64 v[2:3], v[2:3], 0, s[2:3]
	v_cmp_ne_u32_e32 vcc, 0, v6
	v_mov_b32_e32 v5, 0
	s_and_saveexec_b64 s[2:3], vcc
	s_cbranch_execz .LBB0_676
	v_mov_b32_e32 v5, 0
	v_lshlrev_b32_e32 v4, 10, v6
	v_lshl_add_u64 v[4:5], v[2:3], 0, v[4:5]
	global_load_dword v5, v[4:5], off offset:-4
	v_lshlrev_b32_e32 v4, 8, v6

; __device__ __forceinline__ void mlstm_state_scan(const Frame& F) {
;     ...
;     for (int e = gt; e < 1024; e += GT) { const int h = e >> 8; const float* UN = (const float*)(F.ws + WS_UN); float* NST = (float*)(F.ws + WS_NST);
;         float n = 0.f;
;         for (int c = 0; c < NCH; ++c) { NST[c * 1024 + e] = n; n = n * sdec[h * 32 + c] + UN[c * 1024 + e]; }
;         F.out[O_NP + e] = n; }
.LBB0_684:
	v_ashrrev_i32_e32 v0, 3, v16
	v_lshl_add_u64 v[20:21], s[34:35], 0, v[18:19]
	v_lshlrev_b32_e32 v1, 2, v0
	v_add_co_u32_e32 v0, vcc, 0x1ade0000, v20
	v_and_b32_e32 v3, 0xffffff80, v1
	s_nop 0
	v_addc_co_u32_e32 v1, vcc, 0, v21, vcc
	v_add_co_u32_e32 v2, vcc, 0x19dc0000, v20
	v_add_u32_e32 v43, 0, v3
	s_nop 0
	v_addc_co_u32_e32 v3, vcc, 0, v21, vcc
	v_add_co_u32_e32 v40, vcc, 0x1ade1000, v20
	global_store_dword v[0:1], v17, off offset:256
	s_nop 0
	v_addc_co_u32_e32 v41, vcc, 0, v21, vcc
	v_add_co_u32_e32 v42, vcc, 0x19dc1000, v20
	ds_read_b128 v[24:27], v43
	ds_read_b128 v[28:31], v43 offset:16
	v_mov_b32_e32 v104, v170
	ds_read_b128 v[32:35], v43 offset:32
	ds_read_b128 v[36:39], v43 offset:48
	ds_read_b128 v[12:15], v43 offset:64
	ds_read_b128 v[8:11], v43 offset:80
	ds_read_b128 v[4:7], v43 offset:96
	ds_read_b128 v[0:3], v43 offset:112
	v_addc_co_u32_e32 v43, vcc, 0, v21, vcc
	v_add_co_u32_e32 v44, vcc, 0x1ade2000, v20
	v_mov_b32_e32 v105, v171
	s_nop 0
	v_addc_co_u32_e32 v45, vcc, 0, v21, vcc
	v_add_co_u32_e32 v42, vcc, 0x19dc2000, v20
	s_add_u32 s34, s34, s24
	s_nop 0
	v_addc_co_u32_e32 v43, vcc, 0, v21, vcc
	v_add_co_u32_e32 v46, vcc, 0x1ade3000, v20
	v_mov_b32_e32 v106, v172
	s_nop 0
	v_addc_co_u32_e32 v47, vcc, 0, v21, vcc
	v_add_co_u32_e32 v42, vcc, 0x19dc3000, v20
	s_addc_u32 s35, s35, s25
	s_nop 0
	v_addc_co_u32_e32 v43, vcc, 0, v21, vcc
	v_add_co_u32_e32 v48, vcc, 0x1ade4000, v20
	v_mov_b32_e32 v107, v173
	s_nop 0
	v_addc_co_u32_e32 v49, vcc, 0, v21, vcc
	v_add_co_u32_e32 v42, vcc, 0x19dc4000, v20
	v_lshl_add_u64 v[22:23], s[26:27], 0, v[18:19]
	s_nop 0
	v_addc_co_u32_e32 v43, vcc, 0, v21, vcc
	v_add_co_u32_e32 v50, vcc, 0x1ade5000, v20
	v_mov_b32_e32 v108, v174
	s_nop 0
	v_addc_co_u32_e32 v51, vcc, 0, v21, vcc
	v_add_co_u32_e32 v42, vcc, 0x19dc5000, v20
	v_add_u32_e32 v16, s20, v16
	s_nop 0
	v_addc_co_u32_e32 v43, vcc, 0, v21, vcc
	v_add_co_u32_e32 v52, vcc, 0x1ade6000, v20
	v_mov_b32_e32 v109, v175
	s_nop 0
	v_addc_co_u32_e32 v53, vcc, 0, v21, vcc
	v_add_co_u32_e32 v42, vcc, 0x19dc6000, v20
	s_add_u32 s26, s26, s24
	s_nop 0
	v_addc_co_u32_e32 v43, vcc, 0, v21, vcc
	v_add_co_u32_e32 v54, vcc, 0x1ade7000, v20
	v_mov_b32_e32 v110, v176
	s_nop 0
	v_addc_co_u32_e32 v55, vcc, 0, v21, vcc
	v_add_co_u32_e32 v42, vcc, 0x19dc7000, v20
	v_cmp_lt_i32_e64 s[0:1], s21, v16
	s_nop 0
	v_addc_co_u32_e32 v43, vcc, 0, v21, vcc
	v_add_co_u32_e32 v56, vcc, 0x1ade8000, v20
	v_mov_b32_e32 v111, v177
	s_nop 0
	v_addc_co_u32_e32 v57, vcc, 0, v21, vcc
	v_add_co_u32_e32 v42, vcc, 0x19dc8000, v20
	s_addc_u32 s27, s27, s25
	s_nop 0
	v_addc_co_u32_e32 v43, vcc, 0, v21, vcc
	v_add_co_u32_e32 v58, vcc, 0x1ade9000, v20
	v_mov_b32_e32 v112, v178
	s_nop 0
	v_addc_co_u32_e32 v59, vcc, 0, v21, vcc
	v_add_co_u32_e32 v42, vcc, 0x19dc9000, v20
	s_or_b64 s[30:31], s[0:1], s[30:31]
	s_nop 0
	v_addc_co_u32_e32 v43, vcc, 0, v21, vcc
	v_add_co_u32_e32 v60, vcc, 0x1adea000, v20
	v_mov_b32_e32 v113, v179
	s_nop 0
	v_addc_co_u32_e32 v61, vcc, 0, v21, vcc
	v_add_co_u32_e32 v42, vcc, 0x19dca000, v20
	s_waitcnt vmcnt(9) lgkmcnt(7)
	v_fmac_f32_e32 v104, 0, v24
	v_addc_co_u32_e32 v43, vcc, 0, v21, vcc
	v_add_co_u32_e32 v62, vcc, 0x1adeb000, v20
	v_mov_b32_e32 v114, v180
	s_nop 0
	v_addc_co_u32_e32 v63, vcc, 0, v21, vcc
	v_add_co_u32_e32 v42, vcc, 0x19dcb000, v20
	s_waitcnt vmcnt(9)
	v_fmac_f32_e32 v105, v104, v25
	v_addc_co_u32_e32 v43, vcc, 0, v21, vcc
	v_add_co_u32_e32 v64, vcc, 0x1adec000, v20
	v_mov_b32_e32 v115, v181
	s_nop 0
	v_addc_co_u32_e32 v65, vcc, 0, v21, vcc
	v_add_co_u32_e32 v42, vcc, 0x19dcc000, v20
	s_waitcnt vmcnt(9)
	v_fmac_f32_e32 v106, v105, v26
	v_addc_co_u32_e32 v43, vcc, 0, v21, vcc
	v_add_co_u32_e32 v66, vcc, 0x1aded000, v20
	v_mov_b32_e32 v116, v182
	s_nop 0
	v_addc_co_u32_e32 v67, vcc, 0, v21, vcc
	v_add_co_u32_e32 v42, vcc, 0x19dcd000, v20
	s_waitcnt vmcnt(9)
	v_fmac_f32_e32 v107, v106, v27
	v_addc_co_u32_e32 v43, vcc, 0, v21, vcc
	v_add_co_u32_e32 v68, vcc, 0x1adee000, v20
	v_mov_b32_e32 v117, v183
	s_nop 0
	v_addc_co_u32_e32 v69, vcc, 0, v21, vcc
	v_add_co_u32_e32 v42, vcc, 0x19dce000, v20
	s_waitcnt vmcnt(9) lgkmcnt(6)
	v_fmac_f32_e32 v108, v107, v28
	v_addc_co_u32_e32 v43, vcc, 0, v21, vcc
	v_add_co_u32_e32 v70, vcc, 0x1adef000, v20
	v_mov_b32_e32 v118, v184
	s_nop 0
	v_addc_co_u32_e32 v71, vcc, 0, v21, vcc
	v_add_co_u32_e32 v42, vcc, 0x19dcf000, v20
	s_waitcnt vmcnt(9)
	v_fmac_f32_e32 v109, v108, v29
	v_addc_co_u32_e32 v43, vcc, 0, v21, vcc
	v_add_co_u32_e32 v72, vcc, 0x1adf0000, v20
	v_mov_b32_e32 v119, v185
	s_nop 0
	v_addc_co_u32_e32 v73, vcc, 0, v21, vcc
	v_add_co_u32_e32 v42, vcc, 0x19dd0000, v20
	s_waitcnt vmcnt(9)
	v_fmac_f32_e32 v110, v109, v30
	v_addc_co_u32_e32 v43, vcc, 0, v21, vcc
	v_add_co_u32_e32 v74, vcc, 0x1adf1000, v20
	v_mov_b32_e32 v120, v186
	s_nop 0
	v_addc_co_u32_e32 v75, vcc, 0, v21, vcc
	v_add_co_u32_e32 v42, vcc, 0x19dd1000, v20
	s_waitcnt vmcnt(9)
	v_fmac_f32_e32 v111, v110, v31
	v_addc_co_u32_e32 v43, vcc, 0, v21, vcc
	v_add_co_u32_e32 v76, vcc, 0x1adf2000, v20
	v_mov_b32_e32 v121, v187
	s_nop 0
	v_addc_co_u32_e32 v77, vcc, 0, v21, vcc
	v_add_co_u32_e32 v42, vcc, 0x19dd2000, v20
	s_waitcnt vmcnt(9) lgkmcnt(5)
	v_fmac_f32_e32 v112, v111, v32
	v_addc_co_u32_e32 v43, vcc, 0, v21, vcc
	v_add_co_u32_e32 v78, vcc, 0x1adf3000, v20
	v_mov_b32_e32 v122, v188
	s_nop 0
	v_addc_co_u32_e32 v79, vcc, 0, v21, vcc
	v_add_co_u32_e32 v42, vcc, 0x19dd3000, v20
	s_waitcnt vmcnt(9)
; __device__ __forceinline__ void mlstm_state_scan(const Frame& F) {
;     ...
;     for (int e = gt; e < 1024; e += GT) { const int h = e >> 8; const float* UN = (const float*)(F.ws + WS_UN); float* NST = (float*)(F.ws + WS_NST);
;         float n = 0.f;
;         for (int c = 0; c < NCH; ++c) { NST[c * 1024 + e] = n; n = n * sdec[h * 32 + c] + UN[c * 1024 + e]; }
;         F.out[O_NP + e] = n; }
	v_fmac_f32_e32 v113, v112, v33
	v_addc_co_u32_e32 v43, vcc, 0, v21, vcc
	v_add_co_u32_e32 v80, vcc, 0x1adf4000, v20
	v_mov_b32_e32 v123, v189
	s_nop 0
	v_addc_co_u32_e32 v81, vcc, 0, v21, vcc
	v_add_co_u32_e32 v42, vcc, 0x19dd4000, v20
	s_waitcnt vmcnt(9)
	v_fmac_f32_e32 v114, v113, v34
	v_addc_co_u32_e32 v43, vcc, 0, v21, vcc
	v_add_co_u32_e32 v82, vcc, 0x1adf5000, v20
	v_mov_b32_e32 v124, v190
	s_nop 0
	v_addc_co_u32_e32 v83, vcc, 0, v21, vcc
	v_add_co_u32_e32 v42, vcc, 0x19dd5000, v20
	s_waitcnt vmcnt(9)
	v_fmac_f32_e32 v115, v114, v35
	v_addc_co_u32_e32 v43, vcc, 0, v21, vcc
	v_add_co_u32_e32 v84, vcc, 0x1adf6000, v20
	v_mov_b32_e32 v125, v191
	s_nop 0
	v_addc_co_u32_e32 v85, vcc, 0, v21, vcc
	v_add_co_u32_e32 v42, vcc, 0x19dd6000, v20
	s_waitcnt vmcnt(9) lgkmcnt(4)
	v_fmac_f32_e32 v116, v115, v36
	v_addc_co_u32_e32 v43, vcc, 0, v21, vcc
	v_add_co_u32_e32 v86, vcc, 0x1adf7000, v20
	v_mov_b32_e32 v126, v192
	s_mov_b64 s[0:1], vcc
	v_add_co_u32_e32 v42, vcc, 0x19dd7000, v20
	s_waitcnt vmcnt(9)
	v_fmac_f32_e32 v117, v116, v37
	v_addc_co_u32_e32 v43, vcc, 0, v21, vcc
	v_add_co_u32_e32 v88, vcc, 0x1adf8000, v20
	v_mov_b32_e32 v127, v193
	s_mov_b64 s[2:3], vcc
	v_add_co_u32_e32 v42, vcc, 0x19dd8000, v20
	s_waitcnt vmcnt(9)
	v_fmac_f32_e32 v118, v117, v38
	v_addc_co_u32_e32 v43, vcc, 0, v21, vcc
	v_add_co_u32_e32 v90, vcc, 0x1adf9000, v20
	v_mov_b32_e32 v128, v194
	s_mov_b64 s[4:5], vcc
	v_add_co_u32_e32 v42, vcc, 0x19dd9000, v20
	s_waitcnt vmcnt(9)
	v_fmac_f32_e32 v119, v118, v39
	v_addc_co_u32_e32 v43, vcc, 0, v21, vcc
	v_add_co_u32_e32 v92, vcc, 0x1adfa000, v20
	v_mov_b32_e32 v129, v195
	s_mov_b64 s[6:7], vcc
	v_add_co_u32_e32 v42, vcc, 0x19dda000, v20
	s_waitcnt vmcnt(9) lgkmcnt(3)
	v_fmac_f32_e32 v120, v119, v12
	v_addc_co_u32_e32 v43, vcc, 0, v21, vcc
	v_add_co_u32_e32 v94, vcc, 0x1adfb000, v20
	v_mov_b32_e32 v130, v196
	s_mov_b64 s[8:9], vcc
	v_add_co_u32_e32 v42, vcc, 0x19ddb000, v20
	s_waitcnt vmcnt(9)
	v_fmac_f32_e32 v121, v120, v13
	v_addc_co_u32_e32 v43, vcc, 0, v21, vcc
	v_add_co_u32_e32 v96, vcc, 0x1adfc000, v20
	v_mov_b32_e32 v131, v197
	s_mov_b64 s[10:11], vcc
	v_add_co_u32_e32 v42, vcc, 0x19ddc000, v20
	s_waitcnt vmcnt(9)
	v_fmac_f32_e32 v122, v121, v14
	v_addc_co_u32_e32 v43, vcc, 0, v21, vcc
	v_add_co_u32_e32 v98, vcc, 0x1adfd000, v20
	v_mov_b32_e32 v132, v198
	s_mov_b64 s[12:13], vcc
	v_add_co_u32_e32 v42, vcc, 0x19ddd000, v20
	s_waitcnt vmcnt(9)
	v_fmac_f32_e32 v123, v122, v15
	v_addc_co_u32_e32 v43, vcc, 0, v21, vcc
	v_add_co_u32_e32 v100, vcc, 0x1adfe000, v20
	v_mov_b32_e32 v133, v199
	s_mov_b64 s[14:15], vcc
	v_add_co_u32_e32 v42, vcc, 0x19dde000, v20
	s_waitcnt vmcnt(9) lgkmcnt(2)
	v_fmac_f32_e32 v124, v123, v8
	v_addc_co_u32_e32 v43, vcc, 0, v21, vcc
	v_add_co_u32_e32 v102, vcc, 0x1adff000, v20
	v_mov_b32_e32 v134, v200
	s_mov_b64 s[16:17], vcc
	v_add_co_u32_e32 v42, vcc, 0x19ddf000, v20
	s_waitcnt vmcnt(9)
	v_fmac_f32_e32 v125, v124, v9
	v_addc_co_u32_e32 v43, vcc, 0, v21, vcc
	v_mov_b32_e32 v20, v201
	s_waitcnt vmcnt(9)
	v_fmac_f32_e32 v126, v125, v10
	v_addc_co_u32_e64 v87, vcc, 0, v21, s[0:1]
	v_addc_co_u32_e64 v89, vcc, 0, v21, s[2:3]
	v_addc_co_u32_e64 v91, vcc, 0, v21, s[4:5]
	v_addc_co_u32_e64 v93, vcc, 0, v21, s[6:7]
	s_waitcnt vmcnt(8)
	v_fmac_f32_e32 v127, v126, v11
	v_addc_co_u32_e64 v95, vcc, 0, v21, s[8:9]
	v_addc_co_u32_e64 v97, vcc, 0, v21, s[10:11]
	v_addc_co_u32_e64 v99, vcc, 0, v21, s[12:13]
	v_addc_co_u32_e64 v101, vcc, 0, v21, s[14:15]
	s_waitcnt vmcnt(7) lgkmcnt(1)
	v_fmac_f32_e32 v128, v127, v4
	v_addc_co_u32_e64 v103, vcc, 0, v21, s[16:17]
	global_store_dword v[40:41], v104, off offset:256
	global_store_dword v[44:45], v105, off offset:256
	global_store_dword v[46:47], v106, off offset:256
	global_store_dword v[48:49], v107, off offset:256
	global_store_dword v[50:51], v108, off offset:256
	global_store_dword v[52:53], v109, off offset:256
	s_waitcnt vmcnt(12)
	v_fmac_f32_e32 v129, v128, v5
	global_store_dword v[54:55], v110, off offset:256
	global_store_dword v[56:57], v111, off offset:256
	global_store_dword v[58:59], v112, off offset:256
	global_store_dword v[60:61], v113, off offset:256
	global_store_dword v[62:63], v114, off offset:256
	global_store_dword v[64:65], v115, off offset:256
	global_store_dword v[66:67], v116, off offset:256
	global_store_dword v[68:69], v117, off offset:256
	s_waitcnt vmcnt(19)
	v_fmac_f32_e32 v130, v129, v6
	global_store_dword v[70:71], v118, off offset:256
	global_store_dword v[72:73], v119, off offset:256
	global_store_dword v[74:75], v120, off offset:256
	global_store_dword v[76:77], v121, off offset:256
	global_store_dword v[78:79], v122, off offset:256
	global_store_dword v[80:81], v123, off offset:256
	global_store_dword v[82:83], v124, off offset:256
	global_store_dword v[84:85], v125, off offset:256
	s_waitcnt vmcnt(26)
	v_fmac_f32_e32 v131, v130, v7
	global_store_dword v[86:87], v126, off offset:256
	global_store_dword v[88:89], v127, off offset:256
	global_store_dword v[90:91], v128, off offset:256
	global_store_dword v[92:93], v129, off offset:256
	global_store_dword v[94:95], v130, off offset:256
	global_store_dword v[96:97], v131, off offset:256
	s_waitcnt vmcnt(31) lgkmcnt(0)
	v_fmac_f32_e32 v132, v131, v0
	global_store_dword v[98:99], v132, off offset:256
	s_waitcnt vmcnt(31)
	v_fmac_f32_e32 v133, v132, v1
	global_store_dword v[100:101], v133, off offset:256
	s_waitcnt vmcnt(31)
	v_fmac_f32_e32 v134, v133, v2
	global_store_dword v[102:103], v134, off offset:256
	s_waitcnt vmcnt(31)
	v_fmac_f32_e32 v20, v134, v3
	global_store_dword v[22:23], v20, off
	s_andn2_b64 exec, exec, s[30:31]
	s_cbranch_execnz .LBB0_684
